# weight convert rewrite; phase-6 part runs at phase start after a 10 us pause
# speedup vs baseline: 1.0840x; 1.0840x over previous
_Z4mega6Params:
	s_load_dwordx8 s[60:67], s[0:1], 0xa0
	s_load_dwordx8 s[4:11], s[0:1], 0x80
	s_mov_b32 s57, s2
	s_mov_b32 s99, s2
	s_mov_b64 s[100:101], s[0:1]
	v_and_b32_e32 v225, 0x3ff, v0
	s_waitcnt lgkmcnt(0)
	v_writelane_b32 v252, s4, 0
	s_nop 1
	v_writelane_b32 v252, s5, 1
	v_writelane_b32 v252, s6, 2
	v_writelane_b32 v252, s7, 3
	v_writelane_b32 v252, s8, 4
	v_writelane_b32 v252, s9, 5
	v_writelane_b32 v252, s10, 6
	v_writelane_b32 v252, s11, 7
	s_add_u32 s4, s0, 0xc0
	s_addc_u32 s5, s1, 0
	v_cmp_eq_u32_e64 s[6:7], 0, v225
	s_mov_b64 s[2:3], exec
	s_nop 0
	v_writelane_b32 v252, s6, 8
	s_nop 1
	v_writelane_b32 v252, s7, 9
	s_and_b64 s[6:7], s[2:3], s[6:7]
	s_mov_b64 exec, s[6:7]
	v_mov_b32_e32 v2, 0
	v_mov_b32_e32 v3, v2
	v_mov_b32_e32 v4, v2
	v_mov_b32_e32 v5, v2
	ds_write_b128 v2, v[2:5]
	s_or_b64 exec, exec, s[2:3]
	s_load_dwordx2 s[78:79], s[0:1], 0xc0
	s_add_u32 s2, s64, 0x21c0000
	s_addc_u32 s3, s65, 0
	v_writelane_b32 v252, s2, 10
	s_waitcnt lgkmcnt(0)
	s_barrier
	v_writelane_b32 v252, s3, 11
	s_getreg_b32 s2, hwreg(HW_REG_XCC_ID, 0, 4)
	s_and_b32 s10, s2, 15
	s_mov_b64 s[2:3], exec
	v_readlane_b32 s6, v252, 8
	v_readlane_b32 s7, v252, 9
	s_and_b64 s[6:7], s[2:3], s[6:7]
	s_mov_b64 exec, s[6:7]
	s_cbranch_execz .LBB0_5
	s_mov_b64 s[6:7], exec
	v_mbcnt_lo_u32_b32 v1, s6, 0
	v_mbcnt_hi_u32_b32 v1, s7, v1
	v_cmp_eq_u32_e32 vcc, 0, v1
	s_and_b64 s[8:9], exec, vcc
	s_mov_b64 exec, s[8:9]
	s_cbranch_execz .LBB0_5
	s_bcnt1_i32_b64 s6, s[6:7]
	s_lshl_b32 s8, s10, 8
	v_mov_b32_e32 v2, s6
	v_readlane_b32 s6, v252, 10
	v_mov_b32_e32 v1, s8
	v_readlane_b32 s7, v252, 11
	s_nop 4
	global_atomic_add v1, v2, s[6:7] offset:1024

.LBB0_22:
	s_cmp_eq_u32 s66, 6
	s_cbranch_scc0 .Lwt1_skip
	s_cmp_ge_u32 s99, 0x80
	s_cbranch_scc0 .Lwt1_skip
	s_load_dword s98, s[100:101], 0xc0
	s_waitcnt lgkmcnt(0)
	s_cmp_eq_u32 s98, 0x100
	s_cbranch_scc0 .Lwt1_skip
	s_mov_b64 exec, -1
	v_writelane_b32 v59, s16, 0
	v_writelane_b32 v59, s17, 1
	v_writelane_b32 v59, s18, 2
	v_writelane_b32 v59, s19, 3
	v_writelane_b32 v59, s20, 4
	v_writelane_b32 v59, s21, 5
	v_writelane_b32 v59, s22, 6
	v_writelane_b32 v59, s23, 7
	v_writelane_b32 v59, s24, 8
	v_writelane_b32 v59, s25, 9
	v_writelane_b32 v59, s26, 10
	v_writelane_b32 v59, s27, 11
	v_writelane_b32 v59, s28, 12
	v_writelane_b32 v59, s29, 13
	v_writelane_b32 v59, s30, 14
	v_writelane_b32 v59, s31, 15
	v_writelane_b32 v59, s32, 16
	v_writelane_b32 v59, s33, 17
	v_writelane_b32 v59, s34, 18
	v_writelane_b32 v59, s35, 19
	v_writelane_b32 v59, s36, 20
	v_writelane_b32 v59, s37, 21
	v_writelane_b32 v59, s38, 22
	v_writelane_b32 v59, s39, 23
	v_writelane_b32 v59, s40, 24
	v_writelane_b32 v59, s41, 25
	v_writelane_b32 v59, s42, 26
	v_writelane_b32 v59, s43, 27
	v_writelane_b32 v59, s44, 28
	v_writelane_b32 v59, s45, 29
	v_writelane_b32 v59, s46, 30
	v_writelane_b32 v59, s47, 31
	v_writelane_b32 v59, s48, 32
	v_writelane_b32 v59, s49, 33
	v_writelane_b32 v59, s50, 34
	v_writelane_b32 v59, s51, 35
	v_writelane_b32 v59, s52, 36
	v_writelane_b32 v59, s53, 37
	v_writelane_b32 v59, s54, 38
	v_writelane_b32 v59, s55, 39
	s_memrealtime s[40:41]
	s_waitcnt lgkmcnt(0)
	s_add_u32 s42, s40, 1000
.Lwt1_spin:
	s_sleep 4
	s_memrealtime s[40:41]
	s_waitcnt lgkmcnt(0)
	s_sub_u32 s43, s40, s42
	s_cmp_lt_i32 s43, 0
	s_cbranch_scc1 .Lwt1_spin
	v_lshrrev_b32_e32 v60, 6, v225
	v_and_b32_e32 v61, 63, v225
	v_and_b32_e32 v62, 32, v225
	s_load_dwordx2 s[44:45], s[100:101], 0xb0
	v_readfirstlane_b32 s16, v60
	v_add_u32_e32 v62, v62, v61
	v_lshlrev_b32_e32 v60, 2, v61
	s_waitcnt lgkmcnt(0)
	s_movk_i32 s17, 0x400
	s_sub_u32 s18, s99, 0x80
	s_lshl_b32 s18, s18, 3
	s_add_u32 s16, s16, s18
.Lwt1_loop:
	s_cmp_ge_u32 s16, 0xac0
	s_cbranch_scc1 .Lwt1_done
	s_cmp_lt_u32 s16, 0x140
	s_cbranch_scc1 .Lwt1_d0
	s_cmp_lt_u32 s16, 0x180
	s_cbranch_scc1 .Lwt1_d1
	s_cmp_lt_u32 s16, 0x280
	s_cbranch_scc1 .Lwt1_d2
	s_cmp_lt_u32 s16, 0x800
	s_cbranch_scc1 .Lwt1_d3
	s_branch .Lwt1_d4
.Lwt1_d0:
	s_sub_u32 s19, s16, 0x0
	s_mov_b32 s46, 0x70
	s_mov_b32 s47, 0x0
	s_mov_b32 s48, 0x68
	s_mov_b32 s49, 0x0
	s_mov_b32 s50, 0x4200000
	s_mov_b32 s51, 1
	s_mov_b32 s26, 0x1800
	s_mov_b32 s39, 0x60000
	s_mov_b32 s27, 0x800
	s_mov_b32 s28, 0x14
	s_mov_b32 s29, 0xccccccd
	s_mov_b32 s30, 3
	s_mov_b32 s31, 0x0
	s_branch .Lwt1_common
.Lwt1_d1:
	s_sub_u32 s19, s16, 0x140
	s_mov_b32 s46, 0x70
	s_mov_b32 s47, 0x0
	s_mov_b32 s48, 0x68
	s_mov_b32 s49, 0x0
	s_mov_b32 s50, 0x4480000
	s_mov_b32 s51, 1
	s_mov_b32 s26, 0x1800
	s_mov_b32 s39, 0x60000
	s_mov_b32 s27, 0x800
	s_mov_b32 s28, 0x4
	s_mov_b32 s29, 0x40000000
	s_mov_b32 s30, 0
	s_mov_b32 s31, 0x500
	s_branch .Lwt1_common
.Lwt1_d2:
	s_sub_u32 s19, s16, 0x180
	s_mov_b32 s46, 0x88
	s_mov_b32 s47, 0x0
	s_mov_b32 s48, 0x0
	s_mov_b32 s49, 0x0
	s_mov_b32 s50, 0x4500000
	s_mov_b32 s51, 0
	s_mov_b32 s26, 0x1000
	s_mov_b32 s39, 0x40000
	s_mov_b32 s27, 0x800
	s_mov_b32 s28, 0x10
	s_mov_b32 s29, 0x10000000
	s_mov_b32 s30, 0
	s_mov_b32 s31, 0x0
	s_branch .Lwt1_common
.Lwt1_d3:
	s_sub_u32 s19, s16, 0x280
	s_mov_b32 s46, 0x98
	s_mov_b32 s47, 0x1600000
	s_mov_b32 s48, 0x90
	s_mov_b32 s49, 0x1000
	s_mov_b32 s50, 0x4700000
	s_mov_b32 s51, 1
	s_mov_b32 s26, 0x5800
	s_mov_b32 s39, 0x160000
	s_mov_b32 s27, 0x800
	s_mov_b32 s28, 0x58
	s_mov_b32 s29, 0x2e8ba2f
	s_mov_b32 s30, 1
	s_mov_b32 s31, 0x0
	s_branch .Lwt1_common
.Lwt1_d4:
	s_sub_u32 s19, s16, 0x800
	s_mov_b32 s46, 0xa0
	s_mov_b32 s47, 0xb00000
	s_mov_b32 s48, 0x0
	s_mov_b32 s49, 0x0
	s_mov_b32 s50, 0x5200000
	s_mov_b32 s51, 0
	s_mov_b32 s26, 0x1000
	s_mov_b32 s39, 0x40000
	s_mov_b32 s27, 0x1600
	s_mov_b32 s28, 0x10
	s_mov_b32 s29, 0x10000000
	s_mov_b32 s30, 0
	s_mov_b32 s31, 0x0
	s_branch .Lwt1_common
.Lwt1_common:
	s_load_dwordx2 s[20:21], s[100:101], s46
	s_cmp_lg_u32 s51, 0
	s_cbranch_scc0 .Lwt1_nog0
	s_load_dwordx2 s[22:23], s[100:101], s48
.Lwt1_nog0:
	s_mul_hi_u32 s32, s19, s29
	s_mul_i32 s34, s32, s28
	s_sub_u32 s33, s19, s34
	s_add_u32 s24, s44, s50
	s_addc_u32 s25, s45, 0
	s_lshl_b32 s34, s33, 6
	v_add_u32_e32 v63, s34, v61
	v_mul_lo_u32 v71, v63, s27
	s_lshl_b32 s35, s32, 7
	v_add_u32_e32 v71, s35, v71
	s_mov_b64 s[36:37], -1
	s_mov_b32 s38, 0
	s_lshr_b32 s34, s33, 2
	s_bfe_u32 s35, s33, 0x10001
	s_and_b32 s18, s33, 1
	s_cmp_eq_u32 s30, 0
	s_cbranch_scc1 .Lwt1_m_lin
	s_cmp_eq_u32 s30, 1
	s_cbranch_scc1 .Lwt1_m_w13
	s_cmp_eq_u32 s30, 3
	s_cbranch_scc1 .Lwt1_m_pack
	s_cmp_lt_u32 s34, 4
	s_cbranch_scc1 .Lwt1_m_pack
	s_movk_i32 s31, 0x200
	s_cmp_lt_u32 s33, 64
	s_cbranch_scc1 .Lwt1_m_lin
	s_mov_b32 s38, 1
	s_mov_b32 s37, 0
	s_cmp_eq_u32 s33, 64
	s_cselect_b32 s36, -1, 0
.Lwt1_m_lin:
	s_lshl_b32 s34, s33, 6
	s_add_u32 s34, s34, s31
	v_mov_b32_e32 v63, v61
	s_branch .Lwt1_m_done
.Lwt1_m_w13:
	s_mulk_i32 s35, 0xb00
	s_lshl_b32 s34, s34, 7
	s_add_u32 s34, s34, s35
	s_lshl_b32 s18, s18, 6
	s_add_u32 s34, s34, s18
	v_mov_b32_e32 v63, v61
	s_branch .Lwt1_m_done
.Lwt1_m_pack:
	s_lshl_b32 s34, s34, 8
	s_lshl_b32 s18, s18, 7
	s_add_u32 s34, s34, s18
	s_lshl_b32 s35, s35, 5
	s_add_u32 s34, s34, s35
	v_mov_b32_e32 v63, v62
.Lwt1_m_done:
	s_lshl_b32 s34, s34, 2
	s_mul_i32 s35, s32, s39
	s_add_u32 s34, s34, s35
	v_lshl_add_u32 v70, v63, 2, s34
	s_cmp_eq_u32 s38, 0
	s_cbranch_scc1 .Lwt1_nosp0
	v_mov_b32_e32 v64, s35
	v_cndmask_b32_e64 v70, v64, v70, s[36:37]
.Lwt1_nosp0:
	s_waitcnt lgkmcnt(0)
	s_add_u32 s20, s20, s47
	s_addc_u32 s21, s21, 0
	s_cmp_lg_u32 s51, 0
	s_cbranch_scc0 .Lwt1_ld
	s_lshl_b32 s35, s32, 8
	s_add_u32 s35, s35, s49
	s_add_u32 s22, s22, s35
	s_addc_u32 s23, s23, 0
	global_load_dword v69, v60, s[22:23]
.Lwt1_ld:
	global_load_dword v72, v70, s[20:21]
	v_add_u32_e32 v70, s26, v70
	global_load_dword v73, v70, s[20:21]
	v_add_u32_e32 v70, s26, v70
	global_load_dword v74, v70, s[20:21]
	v_add_u32_e32 v70, s26, v70
	global_load_dword v75, v70, s[20:21]
	v_add_u32_e32 v70, s26, v70
	global_load_dword v76, v70, s[20:21]
	v_add_u32_e32 v70, s26, v70
	global_load_dword v77, v70, s[20:21]
	v_add_u32_e32 v70, s26, v70
	global_load_dword v78, v70, s[20:21]
	v_add_u32_e32 v70, s26, v70
	global_load_dword v79, v70, s[20:21]
	v_add_u32_e32 v70, s26, v70
	global_load_dword v80, v70, s[20:21]
	v_add_u32_e32 v70, s26, v70
	global_load_dword v81, v70, s[20:21]
	v_add_u32_e32 v70, s26, v70
	global_load_dword v82, v70, s[20:21]
	v_add_u32_e32 v70, s26, v70
	global_load_dword v83, v70, s[20:21]
	v_add_u32_e32 v70, s26, v70
	global_load_dword v84, v70, s[20:21]
	v_add_u32_e32 v70, s26, v70
	global_load_dword v85, v70, s[20:21]
	v_add_u32_e32 v70, s26, v70
	global_load_dword v86, v70, s[20:21]
	v_add_u32_e32 v70, s26, v70
	global_load_dword v87, v70, s[20:21]
	v_add_u32_e32 v70, s26, v70
	global_load_dword v88, v70, s[20:21]
	v_add_u32_e32 v70, s26, v70
	global_load_dword v89, v70, s[20:21]
	v_add_u32_e32 v70, s26, v70
	global_load_dword v90, v70, s[20:21]
	v_add_u32_e32 v70, s26, v70
	global_load_dword v91, v70, s[20:21]
	v_add_u32_e32 v70, s26, v70
	global_load_dword v92, v70, s[20:21]
	v_add_u32_e32 v70, s26, v70
	global_load_dword v93, v70, s[20:21]
	v_add_u32_e32 v70, s26, v70
	global_load_dword v94, v70, s[20:21]
	v_add_u32_e32 v70, s26, v70
	global_load_dword v95, v70, s[20:21]
	v_add_u32_e32 v70, s26, v70
	global_load_dword v96, v70, s[20:21]
	v_add_u32_e32 v70, s26, v70
	global_load_dword v97, v70, s[20:21]
	v_add_u32_e32 v70, s26, v70
	global_load_dword v98, v70, s[20:21]
	v_add_u32_e32 v70, s26, v70
	global_load_dword v99, v70, s[20:21]
	v_add_u32_e32 v70, s26, v70
	global_load_dword v100, v70, s[20:21]
	v_add_u32_e32 v70, s26, v70
	global_load_dword v101, v70, s[20:21]
	v_add_u32_e32 v70, s26, v70
	global_load_dword v102, v70, s[20:21]
	v_add_u32_e32 v70, s26, v70
	global_load_dword v103, v70, s[20:21]
	v_add_u32_e32 v70, s26, v70
	global_load_dword v104, v70, s[20:21]
	v_add_u32_e32 v70, s26, v70
	global_load_dword v105, v70, s[20:21]
	v_add_u32_e32 v70, s26, v70
	global_load_dword v106, v70, s[20:21]
	v_add_u32_e32 v70, s26, v70
	global_load_dword v107, v70, s[20:21]
	v_add_u32_e32 v70, s26, v70
	global_load_dword v108, v70, s[20:21]
	v_add_u32_e32 v70, s26, v70
	global_load_dword v109, v70, s[20:21]
	v_add_u32_e32 v70, s26, v70
	global_load_dword v110, v70, s[20:21]
	v_add_u32_e32 v70, s26, v70
	global_load_dword v111, v70, s[20:21]
	v_add_u32_e32 v70, s26, v70
	global_load_dword v112, v70, s[20:21]
	v_add_u32_e32 v70, s26, v70
	global_load_dword v113, v70, s[20:21]
	v_add_u32_e32 v70, s26, v70
	global_load_dword v114, v70, s[20:21]
	v_add_u32_e32 v70, s26, v70
	global_load_dword v115, v70, s[20:21]
	v_add_u32_e32 v70, s26, v70
	global_load_dword v116, v70, s[20:21]
	v_add_u32_e32 v70, s26, v70
	global_load_dword v117, v70, s[20:21]
	v_add_u32_e32 v70, s26, v70
	global_load_dword v118, v70, s[20:21]
	v_add_u32_e32 v70, s26, v70
	global_load_dword v119, v70, s[20:21]
	v_add_u32_e32 v70, s26, v70
	s_waitcnt vmcnt(32)
	global_load_dword v120, v70, s[20:21]
	v_add_u32_e32 v70, s26, v70
	global_load_dword v121, v70, s[20:21]
	v_add_u32_e32 v70, s26, v70
	global_load_dword v122, v70, s[20:21]
	v_add_u32_e32 v70, s26, v70
	global_load_dword v123, v70, s[20:21]
	v_add_u32_e32 v70, s26, v70
	global_load_dword v124, v70, s[20:21]
	v_add_u32_e32 v70, s26, v70
	global_load_dword v125, v70, s[20:21]
	v_add_u32_e32 v70, s26, v70
	global_load_dword v126, v70, s[20:21]
	v_add_u32_e32 v70, s26, v70
	global_load_dword v127, v70, s[20:21]
	v_add_u32_e32 v70, s26, v70
	global_load_dword v128, v70, s[20:21]
	v_add_u32_e32 v70, s26, v70
	global_load_dword v129, v70, s[20:21]
	v_add_u32_e32 v70, s26, v70
	global_load_dword v130, v70, s[20:21]
	v_add_u32_e32 v70, s26, v70
	global_load_dword v131, v70, s[20:21]
	v_add_u32_e32 v70, s26, v70
	global_load_dword v132, v70, s[20:21]
	v_add_u32_e32 v70, s26, v70
	global_load_dword v133, v70, s[20:21]
	v_add_u32_e32 v70, s26, v70
	global_load_dword v134, v70, s[20:21]
	v_add_u32_e32 v70, s26, v70
	global_load_dword v135, v70, s[20:21]
	s_cmp_lg_u32 s51, 0
	s_cbranch_scc0 .Lwt1_cvt
	v_readlane_b32 s40, v69, 0
	v_readlane_b32 s41, v69, 1
	v_readlane_b32 s42, v69, 2
	v_readlane_b32 s43, v69, 3
	v_mul_f32_e32 v72, s40, v72
	v_readlane_b32 s40, v69, 4
	v_mul_f32_e32 v73, s41, v73
	v_readlane_b32 s41, v69, 5
	v_mul_f32_e32 v74, s42, v74
	v_readlane_b32 s42, v69, 6
	v_mul_f32_e32 v75, s43, v75
	v_readlane_b32 s43, v69, 7
	v_mul_f32_e32 v76, s40, v76
	v_readlane_b32 s40, v69, 8
	v_mul_f32_e32 v77, s41, v77
	v_readlane_b32 s41, v69, 9
	v_mul_f32_e32 v78, s42, v78
	v_readlane_b32 s42, v69, 10
	v_mul_f32_e32 v79, s43, v79
	v_readlane_b32 s43, v69, 11
	v_mul_f32_e32 v80, s40, v80
	v_readlane_b32 s40, v69, 12
	v_mul_f32_e32 v81, s41, v81
	v_readlane_b32 s41, v69, 13
	v_mul_f32_e32 v82, s42, v82
	v_readlane_b32 s42, v69, 14
	v_mul_f32_e32 v83, s43, v83
	v_readlane_b32 s43, v69, 15
	v_mul_f32_e32 v84, s40, v84
	v_readlane_b32 s40, v69, 16
	v_mul_f32_e32 v85, s41, v85
	v_readlane_b32 s41, v69, 17
	v_mul_f32_e32 v86, s42, v86
	v_readlane_b32 s42, v69, 18
	v_mul_f32_e32 v87, s43, v87
	v_readlane_b32 s43, v69, 19
	s_waitcnt vmcnt(32)
	v_mul_f32_e32 v88, s40, v88
	v_readlane_b32 s40, v69, 20
	v_mul_f32_e32 v89, s41, v89
	v_readlane_b32 s41, v69, 21
	v_mul_f32_e32 v90, s42, v90
	v_readlane_b32 s42, v69, 22
	v_mul_f32_e32 v91, s43, v91
	v_readlane_b32 s43, v69, 23
	v_mul_f32_e32 v92, s40, v92
	v_readlane_b32 s40, v69, 24
	v_mul_f32_e32 v93, s41, v93
	v_readlane_b32 s41, v69, 25
	v_mul_f32_e32 v94, s42, v94
	v_readlane_b32 s42, v69, 26
	v_mul_f32_e32 v95, s43, v95
	v_readlane_b32 s43, v69, 27
	v_mul_f32_e32 v96, s40, v96
	v_readlane_b32 s40, v69, 28
	v_mul_f32_e32 v97, s41, v97
	v_readlane_b32 s41, v69, 29
	v_mul_f32_e32 v98, s42, v98
	v_readlane_b32 s42, v69, 30
	v_mul_f32_e32 v99, s43, v99
	v_readlane_b32 s43, v69, 31
	v_mul_f32_e32 v100, s40, v100
	v_readlane_b32 s40, v69, 32
	v_mul_f32_e32 v101, s41, v101
	v_readlane_b32 s41, v69, 33
	v_mul_f32_e32 v102, s42, v102
	v_readlane_b32 s42, v69, 34
	v_mul_f32_e32 v103, s43, v103
	v_readlane_b32 s43, v69, 35
	s_waitcnt vmcnt(16)
	v_mul_f32_e32 v104, s40, v104
	v_readlane_b32 s40, v69, 36
	v_mul_f32_e32 v105, s41, v105
	v_readlane_b32 s41, v69, 37
	v_mul_f32_e32 v106, s42, v106
	v_readlane_b32 s42, v69, 38
	v_mul_f32_e32 v107, s43, v107
	v_readlane_b32 s43, v69, 39
	v_mul_f32_e32 v108, s40, v108
	v_readlane_b32 s40, v69, 40
	v_mul_f32_e32 v109, s41, v109
	v_readlane_b32 s41, v69, 41
	v_mul_f32_e32 v110, s42, v110
	v_readlane_b32 s42, v69, 42
	v_mul_f32_e32 v111, s43, v111
	v_readlane_b32 s43, v69, 43
	v_mul_f32_e32 v112, s40, v112
	v_readlane_b32 s40, v69, 44
	v_mul_f32_e32 v113, s41, v113
	v_readlane_b32 s41, v69, 45
	v_mul_f32_e32 v114, s42, v114
	v_readlane_b32 s42, v69, 46
	v_mul_f32_e32 v115, s43, v115
	v_readlane_b32 s43, v69, 47
	v_mul_f32_e32 v116, s40, v116
	v_readlane_b32 s40, v69, 48
	v_mul_f32_e32 v117, s41, v117
	v_readlane_b32 s41, v69, 49
	v_mul_f32_e32 v118, s42, v118
	v_readlane_b32 s42, v69, 50
	v_mul_f32_e32 v119, s43, v119
	v_readlane_b32 s43, v69, 51
	s_waitcnt vmcnt(0)
	v_mul_f32_e32 v120, s40, v120
	v_readlane_b32 s40, v69, 52
	v_mul_f32_e32 v121, s41, v121
	v_readlane_b32 s41, v69, 53
	v_mul_f32_e32 v122, s42, v122
	v_readlane_b32 s42, v69, 54
	v_mul_f32_e32 v123, s43, v123
	v_readlane_b32 s43, v69, 55
	v_mul_f32_e32 v124, s40, v124
	v_readlane_b32 s40, v69, 56
	v_mul_f32_e32 v125, s41, v125
	v_readlane_b32 s41, v69, 57
	v_mul_f32_e32 v126, s42, v126
	v_readlane_b32 s42, v69, 58
	v_mul_f32_e32 v127, s43, v127
	v_readlane_b32 s43, v69, 59
	v_mul_f32_e32 v128, s40, v128
	v_readlane_b32 s40, v69, 60
	v_mul_f32_e32 v129, s41, v129
	v_readlane_b32 s41, v69, 61
	v_mul_f32_e32 v130, s42, v130
	v_readlane_b32 s42, v69, 62
	v_mul_f32_e32 v131, s43, v131
	v_readlane_b32 s43, v69, 63
	v_mul_f32_e32 v132, s40, v132
	v_mul_f32_e32 v133, s41, v133
	v_mul_f32_e32 v134, s42, v134
	v_mul_f32_e32 v135, s43, v135
.Lwt1_cvt:
	s_waitcnt vmcnt(0)
	v_cvt_pk_bf16_f32 v72, v72, v73
	v_cvt_pk_bf16_f32 v73, v74, v75
	v_cvt_pk_bf16_f32 v74, v76, v77
	v_cvt_pk_bf16_f32 v75, v78, v79
	v_cvt_pk_bf16_f32 v76, v80, v81
	v_cvt_pk_bf16_f32 v77, v82, v83
	v_cvt_pk_bf16_f32 v78, v84, v85
	v_cvt_pk_bf16_f32 v79, v86, v87
	v_cvt_pk_bf16_f32 v80, v88, v89
	v_cvt_pk_bf16_f32 v81, v90, v91
	v_cvt_pk_bf16_f32 v82, v92, v93
	v_cvt_pk_bf16_f32 v83, v94, v95
	v_cvt_pk_bf16_f32 v84, v96, v97
	v_cvt_pk_bf16_f32 v85, v98, v99
	v_cvt_pk_bf16_f32 v86, v100, v101
	v_cvt_pk_bf16_f32 v87, v102, v103
	v_cvt_pk_bf16_f32 v88, v104, v105
	v_cvt_pk_bf16_f32 v89, v106, v107
	v_cvt_pk_bf16_f32 v90, v108, v109
	v_cvt_pk_bf16_f32 v91, v110, v111
	v_cvt_pk_bf16_f32 v92, v112, v113
	v_cvt_pk_bf16_f32 v93, v114, v115
	v_cvt_pk_bf16_f32 v94, v116, v117
	v_cvt_pk_bf16_f32 v95, v118, v119
	v_cvt_pk_bf16_f32 v96, v120, v121
	v_cvt_pk_bf16_f32 v97, v122, v123
	v_cvt_pk_bf16_f32 v98, v124, v125
	v_cvt_pk_bf16_f32 v99, v126, v127
	v_cvt_pk_bf16_f32 v100, v128, v129
	v_cvt_pk_bf16_f32 v101, v130, v131
	v_cvt_pk_bf16_f32 v102, v132, v133
	v_cvt_pk_bf16_f32 v103, v134, v135
	s_cmp_eq_u32 s38, 0
	s_cbranch_scc1 .Lwt1_st
	v_cndmask_b32_e64 v72, 0, v72, s[36:37]
	v_cndmask_b32_e64 v73, 0, v73, s[36:37]
	v_cndmask_b32_e64 v74, 0, v74, s[36:37]
	v_cndmask_b32_e64 v75, 0, v75, s[36:37]
	v_cndmask_b32_e64 v76, 0, v76, s[36:37]
	v_cndmask_b32_e64 v77, 0, v77, s[36:37]
	v_cndmask_b32_e64 v78, 0, v78, s[36:37]
	v_cndmask_b32_e64 v79, 0, v79, s[36:37]
	v_cndmask_b32_e64 v80, 0, v80, s[36:37]
	v_cndmask_b32_e64 v81, 0, v81, s[36:37]
	v_cndmask_b32_e64 v82, 0, v82, s[36:37]
	v_cndmask_b32_e64 v83, 0, v83, s[36:37]
	v_cndmask_b32_e64 v84, 0, v84, s[36:37]
	v_cndmask_b32_e64 v85, 0, v85, s[36:37]
	v_cndmask_b32_e64 v86, 0, v86, s[36:37]
	v_cndmask_b32_e64 v87, 0, v87, s[36:37]
	v_cndmask_b32_e64 v88, 0, v88, s[36:37]
	v_cndmask_b32_e64 v89, 0, v89, s[36:37]
	v_cndmask_b32_e64 v90, 0, v90, s[36:37]
	v_cndmask_b32_e64 v91, 0, v91, s[36:37]
	v_cndmask_b32_e64 v92, 0, v92, s[36:37]
	v_cndmask_b32_e64 v93, 0, v93, s[36:37]
	v_cndmask_b32_e64 v94, 0, v94, s[36:37]
	v_cndmask_b32_e64 v95, 0, v95, s[36:37]
	v_cndmask_b32_e64 v96, 0, v96, s[36:37]
	v_cndmask_b32_e64 v97, 0, v97, s[36:37]
	v_cndmask_b32_e64 v98, 0, v98, s[36:37]
	v_cndmask_b32_e64 v99, 0, v99, s[36:37]
	v_cndmask_b32_e64 v100, 0, v100, s[36:37]
	v_cndmask_b32_e64 v101, 0, v101, s[36:37]
	v_cndmask_b32_e64 v102, 0, v102, s[36:37]
	v_cndmask_b32_e64 v103, 0, v103, s[36:37]
.Lwt1_st:
	global_store_dwordx4 v71, v[72:75], s[24:25]
	global_store_dwordx4 v71, v[76:79], s[24:25] offset:16
	global_store_dwordx4 v71, v[80:83], s[24:25] offset:32
	global_store_dwordx4 v71, v[84:87], s[24:25] offset:48
	global_store_dwordx4 v71, v[88:91], s[24:25] offset:64
	global_store_dwordx4 v71, v[92:95], s[24:25] offset:80
	global_store_dwordx4 v71, v[96:99], s[24:25] offset:96
	global_store_dwordx4 v71, v[100:103], s[24:25] offset:112
	s_add_u32 s16, s16, s17
	s_branch .Lwt1_loop
.Lwt1_done:
	v_readlane_b32 s16, v59, 0
	v_readlane_b32 s17, v59, 1
	v_readlane_b32 s18, v59, 2
	v_readlane_b32 s19, v59, 3
	v_readlane_b32 s20, v59, 4
	v_readlane_b32 s21, v59, 5
	v_readlane_b32 s22, v59, 6
	v_readlane_b32 s23, v59, 7
	v_readlane_b32 s24, v59, 8
	v_readlane_b32 s25, v59, 9
	v_readlane_b32 s26, v59, 10
	v_readlane_b32 s27, v59, 11
	v_readlane_b32 s28, v59, 12
	v_readlane_b32 s29, v59, 13
	v_readlane_b32 s30, v59, 14
	v_readlane_b32 s31, v59, 15
	v_readlane_b32 s32, v59, 16
	v_readlane_b32 s33, v59, 17
	v_readlane_b32 s34, v59, 18
	v_readlane_b32 s35, v59, 19
	v_readlane_b32 s36, v59, 20
	v_readlane_b32 s37, v59, 21
	v_readlane_b32 s38, v59, 22
	v_readlane_b32 s39, v59, 23
	v_readlane_b32 s40, v59, 24
	v_readlane_b32 s41, v59, 25
	v_readlane_b32 s42, v59, 26
	v_readlane_b32 s43, v59, 27
	v_readlane_b32 s44, v59, 28
	v_readlane_b32 s45, v59, 29
	v_readlane_b32 s46, v59, 30
	v_readlane_b32 s47, v59, 31
	v_readlane_b32 s48, v59, 32
	v_readlane_b32 s49, v59, 33
	v_readlane_b32 s50, v59, 34
	v_readlane_b32 s51, v59, 35
	v_readlane_b32 s52, v59, 36
	v_readlane_b32 s53, v59, 37
	v_readlane_b32 s54, v59, 38
	v_readlane_b32 s55, v59, 39

.LBB0_623:
	v_readlane_b32 s0, v254, 46
	v_readlane_b32 s1, v254, 47
	v_readlane_b32 s18, v255, 26
	v_readlane_b32 s20, v255, 28
	v_readlane_b32 s26, v255, 30
	v_readlane_b32 s28, v255, 32
	s_andn2_b64 vcc, exec, s[0:1]
	s_movk_i32 s72, 0x17f
	s_movk_i32 s76, 0xb00
	s_mov_b64 s[92:93], 0x10000
	v_readlane_b32 s19, v255, 27
	v_readlane_b32 s21, v255, 29
	v_readlane_b32 s27, v255, 31
	v_readlane_b32 s29, v255, 33
	s_cbranch_vccnz .LBB0_31
	s_branch .LBB0_31

.LBB0_1115:
	s_and_b64 vcc, exec, s[0:1]
	s_cbranch_vccz .LBB0_1303
	s_cmp_eq_u32 s66, 0
	s_cbranch_scc0 .LBB0_1303
	s_mov_b64 s[2:3], 0
	v_mov_b32_e32 v68, v225
	v_readlane_b32 s4, v252, 60
	v_ashrrev_i32_e32 v0, 6, v68
	s_add_u32 s0, s64, s2
	v_add_u32_e32 v13, s4, v0
	s_movk_i32 s4, 0xe80
	s_addc_u32 s1, s65, s3
	v_and_b32_e32 v12, 63, v68
	v_cmp_gt_i32_e32 vcc, s4, v13
	s_mov_b64 s[4:5], exec
	s_mov_b64 exec, -1
	v_writelane_b32 v59, s16, 0
	v_writelane_b32 v59, s17, 1
	v_writelane_b32 v59, s18, 2
	v_writelane_b32 v59, s19, 3
	v_writelane_b32 v59, s20, 4
	v_writelane_b32 v59, s21, 5
	v_writelane_b32 v59, s22, 6
	v_writelane_b32 v59, s23, 7
	v_writelane_b32 v59, s24, 8
	v_writelane_b32 v59, s25, 9
	v_writelane_b32 v59, s26, 10
	v_writelane_b32 v59, s27, 11
	v_writelane_b32 v59, s28, 12
	v_writelane_b32 v59, s29, 13
	v_writelane_b32 v59, s30, 14
	v_writelane_b32 v59, s31, 15
	v_writelane_b32 v59, s32, 16
	v_writelane_b32 v59, s33, 17
	v_writelane_b32 v59, s34, 18
	v_writelane_b32 v59, s35, 19
	v_writelane_b32 v59, s36, 20
	v_writelane_b32 v59, s37, 21
	v_writelane_b32 v59, s38, 22
	v_writelane_b32 v59, s39, 23
	v_writelane_b32 v59, s40, 24
	v_writelane_b32 v59, s41, 25
	v_writelane_b32 v59, s42, 26
	v_writelane_b32 v59, s43, 27
	v_writelane_b32 v59, s44, 28
	v_writelane_b32 v59, s45, 29
	v_writelane_b32 v59, s46, 30
	v_writelane_b32 v59, s47, 31
	v_writelane_b32 v59, s48, 32
	v_writelane_b32 v59, s49, 33
	v_writelane_b32 v59, s50, 34
	v_writelane_b32 v59, s51, 35
	v_writelane_b32 v59, s52, 36
	v_writelane_b32 v59, s53, 37
	v_writelane_b32 v59, s54, 38
	v_writelane_b32 v59, s55, 39
	v_lshrrev_b32_e32 v60, 6, v225
	v_and_b32_e32 v61, 63, v225
	v_and_b32_e32 v62, 32, v225
	s_load_dwordx2 s[44:45], s[100:101], 0xb0
	s_load_dword s17, s[100:101], 0xc0
	v_readfirstlane_b32 s16, v60
	v_add_u32_e32 v62, v62, v61
	v_lshlrev_b32_e32 v60, 2, v61
	s_waitcnt lgkmcnt(0)
	s_lshl_b32 s17, s17, 3
	s_lshl_b32 s18, s99, 3
	s_add_u32 s16, s16, s18
.Lwt0_loop:
	s_cmp_ge_u32 s16, 0xe80
	s_cbranch_scc1 .Lwt0_done
	s_cmp_lt_u32 s16, 0x440
	s_cbranch_scc1 .Lwt0_d0
	s_cmp_lt_u32 s16, 0x4c0
	s_cbranch_scc1 .Lwt0_d1
	s_cmp_lt_u32 s16, 0x640
	s_cbranch_scc1 .Lwt0_d2
	s_cmp_lt_u32 s16, 0xbc0
	s_cbranch_scc1 .Lwt0_d3
	s_branch .Lwt0_d4
.Lwt0_d0:
	s_sub_u32 s19, s16, 0x0
	s_mov_b32 s46, 0x10
	s_mov_b32 s47, 0x0
	s_mov_b32 s48, 0x8
	s_mov_b32 s49, 0x0
	s_mov_b32 s50, 0x0
	s_mov_b32 s51, 1
	s_mov_b32 s26, 0x4880
	s_mov_b32 s39, 0x122000
	s_mov_b32 s27, 0x800
	s_mov_b32 s28, 0x44
	s_mov_b32 s29, 0x3c3c3c4
	s_mov_b32 s30, 2
	s_mov_b32 s31, 0x0
	s_branch .Lwt0_common
.Lwt0_d1:
	s_sub_u32 s19, s16, 0x440
	s_mov_b32 s46, 0x10
	s_mov_b32 s47, 0x0
	s_mov_b32 s48, 0x8
	s_mov_b32 s49, 0x0
	s_mov_b32 s50, 0x880000
	s_mov_b32 s51, 1
	s_mov_b32 s26, 0x4880
	s_mov_b32 s39, 0x122000
	s_mov_b32 s27, 0x800
	s_mov_b32 s28, 0x8
	s_mov_b32 s29, 0x20000000
	s_mov_b32 s30, 0
	s_mov_b32 s31, 0x400
	s_branch .Lwt0_common
.Lwt0_d2:
	s_sub_u32 s19, s16, 0x4c0
	s_mov_b32 s46, 0x60
	s_mov_b32 s47, 0x0
	s_mov_b32 s48, 0x0
	s_mov_b32 s49, 0x0
	s_mov_b32 s50, 0x980000
	s_mov_b32 s51, 0
	s_mov_b32 s26, 0x1000
	s_mov_b32 s39, 0x40000
	s_mov_b32 s27, 0xc00
	s_mov_b32 s28, 0x10
	s_mov_b32 s29, 0x10000000
	s_mov_b32 s30, 0
	s_mov_b32 s31, 0x0
	s_branch .Lwt0_common
.Lwt0_d3:
	s_sub_u32 s19, s16, 0x640
	s_mov_b32 s46, 0x98
	s_mov_b32 s47, 0x0
	s_mov_b32 s48, 0x90
	s_mov_b32 s49, 0x0
	s_mov_b32 s50, 0xc80000
	s_mov_b32 s51, 1
	s_mov_b32 s26, 0x5800
	s_mov_b32 s39, 0x160000
	s_mov_b32 s27, 0x800
	s_mov_b32 s28, 0x58
	s_mov_b32 s29, 0x2e8ba2f
	s_mov_b32 s30, 1
	s_mov_b32 s31, 0x0
	s_branch .Lwt0_common
.Lwt0_d4:
	s_sub_u32 s19, s16, 0xbc0
	s_mov_b32 s46, 0xa0
	s_mov_b32 s47, 0x0
	s_mov_b32 s48, 0x0
	s_mov_b32 s49, 0x0
	s_mov_b32 s50, 0x1780000
	s_mov_b32 s51, 0
	s_mov_b32 s26, 0x1000
	s_mov_b32 s39, 0x40000
	s_mov_b32 s27, 0x1600
	s_mov_b32 s28, 0x10
	s_mov_b32 s29, 0x10000000
	s_mov_b32 s30, 0
	s_mov_b32 s31, 0x0
	s_branch .Lwt0_common

.Lwt0_done:
	v_readlane_b32 s16, v59, 0
	v_readlane_b32 s17, v59, 1
	v_readlane_b32 s18, v59, 2
	v_readlane_b32 s19, v59, 3
	v_readlane_b32 s20, v59, 4
	v_readlane_b32 s21, v59, 5
	v_readlane_b32 s22, v59, 6
	v_readlane_b32 s23, v59, 7
	v_readlane_b32 s24, v59, 8
	v_readlane_b32 s25, v59, 9
	v_readlane_b32 s26, v59, 10
	v_readlane_b32 s27, v59, 11
	v_readlane_b32 s28, v59, 12
	v_readlane_b32 s29, v59, 13
	v_readlane_b32 s30, v59, 14
	v_readlane_b32 s31, v59, 15
	v_readlane_b32 s32, v59, 16
	v_readlane_b32 s33, v59, 17
	v_readlane_b32 s34, v59, 18
	v_readlane_b32 s35, v59, 19
	v_readlane_b32 s36, v59, 20
	v_readlane_b32 s37, v59, 21
	v_readlane_b32 s38, v59, 22
	v_readlane_b32 s39, v59, 23
	v_readlane_b32 s40, v59, 24
	v_readlane_b32 s41, v59, 25
	v_readlane_b32 s42, v59, 26
	v_readlane_b32 s43, v59, 27
	v_readlane_b32 s44, v59, 28
	v_readlane_b32 s45, v59, 29
	v_readlane_b32 s46, v59, 30
	v_readlane_b32 s47, v59, 31
	v_readlane_b32 s48, v59, 32
	v_readlane_b32 s49, v59, 33
	v_readlane_b32 s50, v59, 34
	v_readlane_b32 s51, v59, 35
	v_readlane_b32 s52, v59, 36
	v_readlane_b32 s53, v59, 37
	v_readlane_b32 s54, v59, 38
	v_readlane_b32 s55, v59, 39
	s_branch .LBB0_1344

	.amdhsa_kernel _Z4mega6Params
		.amdhsa_group_segment_fixed_size 16
		.amdhsa_private_segment_fixed_size 0
		.amdhsa_kernarg_size 448
		.amdhsa_user_sgpr_count 2
		.amdhsa_user_sgpr_dispatch_ptr 0
		.amdhsa_user_sgpr_queue_ptr 0
		.amdhsa_user_sgpr_kernarg_segment_ptr 1
		.amdhsa_user_sgpr_dispatch_id 0
		.amdhsa_user_sgpr_kernarg_preload_length 0
		.amdhsa_user_sgpr_kernarg_preload_offset 0
		.amdhsa_user_sgpr_private_segment_size 0
		.amdhsa_uses_dynamic_stack 0
		.amdhsa_enable_private_segment 0
		.amdhsa_system_sgpr_workgroup_id_x 1
		.amdhsa_system_sgpr_workgroup_id_y 0
		.amdhsa_system_sgpr_workgroup_id_z 0
		.amdhsa_system_sgpr_workgroup_info 0
		.amdhsa_system_vgpr_workitem_id 2
		.amdhsa_next_free_vgpr 256
		.amdhsa_next_free_sgpr 102
		.amdhsa_accum_offset 256
		.amdhsa_reserve_vcc 1
		.amdhsa_float_round_mode_32 0
		.amdhsa_float_round_mode_16_64 0
		.amdhsa_float_denorm_mode_32 3
		.amdhsa_float_denorm_mode_16_64 3
		.amdhsa_dx10_clamp 1
		.amdhsa_ieee_mode 1
		.amdhsa_fp16_overflow 0
		.amdhsa_tg_split 0
		.amdhsa_exception_fp_ieee_invalid_op 0
		.amdhsa_exception_fp_denorm_src 0
		.amdhsa_exception_fp_ieee_div_zero 0
		.amdhsa_exception_fp_ieee_overflow 0
		.amdhsa_exception_fp_ieee_underflow 0
		.amdhsa_exception_fp_ieee_inexact 0
		.amdhsa_exception_int_div_zero 0
	.end_amdhsa_kernel

amdhsa.kernels:
  - .agpr_count:     0
    .args:
      - .offset:         0
        .size:           192
        .value_kind:     by_value
      - .offset:         192
        .size:           4
        .value_kind:     hidden_block_count_x
      - .offset:         196
        .size:           4
        .value_kind:     hidden_block_count_y
      - .offset:         200
        .size:           4
        .value_kind:     hidden_block_count_z
      - .offset:         204
        .size:           2
        .value_kind:     hidden_group_size_x
      - .offset:         206
        .size:           2
        .value_kind:     hidden_group_size_y
      - .offset:         208
        .size:           2
        .value_kind:     hidden_group_size_z
      - .offset:         210
        .size:           2
        .value_kind:     hidden_remainder_x
      - .offset:         212
        .size:           2
        .value_kind:     hidden_remainder_y
      - .offset:         214
        .size:           2
        .value_kind:     hidden_remainder_z
      - .offset:         232
        .size:           8
        .value_kind:     hidden_global_offset_x
      - .offset:         240
        .size:           8
        .value_kind:     hidden_global_offset_y
      - .offset:         248
        .size:           8
        .value_kind:     hidden_global_offset_z
      - .offset:         256
        .size:           2
        .value_kind:     hidden_grid_dims
      - .offset:         280
        .size:           8
        .value_kind:     hidden_multigrid_sync_arg
      - .offset:         312
        .size:           4
        .value_kind:     hidden_dynamic_lds_size
    .group_segment_fixed_size: 16
    .kernarg_segment_align: 8
    .kernarg_segment_size: 448
    .language:       OpenCL C
    .language_version:
      - 2
      - 0
    .max_flat_workgroup_size: 512
    .name:           _Z4mega6Params
    .private_segment_fixed_size: 0
    .sgpr_count:     108
    .sgpr_spill_count: 266
    .symbol:         _Z4mega6Params.kd
    .uniform_work_group_size: 1
    .uses_dynamic_stack: false
    .vgpr_count:     256
    .vgpr_spill_count: 0
    .wavefront_size: 64
